# phases 5/6 interleaved: workgroups with blockIdx bit 3 set run the long convolution before their retention-output items (others keep ret_out then conv), so memory-bound and MFMA-bound work overlap acr
# speedup vs baseline: 1.0228x; 1.0054x over previous
.LBB0_899:
	s_mov_b32 s100, 0
	s_cmp_lt_i32 s92, 7
	s_cselect_b64 s[24:25], -1, 0
	s_cmp_gt_i32 s92, 6
	s_cselect_b64 s[0:1], -1, 0
	s_cmp_lt_i32 s93, 7
	s_cselect_b64 s[4:5], -1, 0
	s_or_b64 s[0:1], s[0:1], s[4:5]
	s_and_b64 vcc, exec, s[0:1]
	s_cbranch_vccnz .LBB0_905
	s_cmpk_gt_i32 s20, 0x3ff
	s_cbranch_scc1 .LBB0_905
	s_cmp_lg_u32 s34, 0x100
	s_cbranch_scc1 .Lp6_retout_entry
	s_bitcmp0_b32 s20, 3
	s_cbranch_scc1 .Lp6_retout_entry
	s_mov_b32 s100, 1
	v_writelane_b32 v254, s54, 0
	v_writelane_b32 v254, s55, 1
	v_writelane_b32 v254, s56, 2
	v_writelane_b32 v254, s57, 3
	s_branch .LBB0_905
.Lp6_retout_entry:
	s_add_u32 s0, s22, 0x74bc000
	s_addc_u32 s1, s23, 0
	s_add_u32 s11, s22, 0x154bc000
	s_addc_u32 s13, s23, 0
	s_add_i32 s10, 0, 0x1b000
	s_ashr_i32 s6, s20, 7
	s_waitcnt vmcnt(0)
	v_lshrrev_b32_e32 v42, 6, v160
	s_movk_i32 s4, 0x1400
	v_mov_b32_e32 v0, s10
	s_and_b32 s16, s20, 31
	s_ashr_i32 s7, s6, 31
	v_mad_u32_u24 v73, v42, s4, v0
	s_lshl_b64 s[8:9], s[6:7], 12
	s_lshl_b32 s4, s16, 7
	s_or_b32 s8, s8, s4
	s_mul_i32 s4, s9, 0x1c00
	s_mul_hi_u32 s7, s8, 0x1c00
	s_bfe_u32 s12, s20, 0x20005
	s_add_i32 s7, s7, s4
	s_mul_i32 s4, s8, 0x1c00
	s_add_u32 s14, s0, s4
	s_addc_u32 s7, s1, s7
	s_lshl_b32 s4, s12, 8
	s_add_u32 s14, s14, s4
	s_addc_u32 s15, s7, 0
	s_lshl_b32 s6, s6, 2
	s_ashr_i32 s7, s6, 31
	s_or_b32 s6, s6, s12
	v_and_b32_e32 v162, 15, v160
	v_lshrrev_b32_e32 v164, 4, v160
	s_lshl_b64 s[6:7], s[6:7], 20
	s_add_u32 s6, s11, s6
	v_mov_b32_e32 v167, 0
	v_lshlrev_b32_e32 v166, 4, v162
	v_mul_u32_u24_e32 v68, 0xe00, v164
	s_addc_u32 s7, s13, s7
	s_lshl_b32 s12, s16, 15
	v_lshl_add_u64 v[0:1], s[14:15], 0, v[166:167]
	v_lshlrev_b32_e32 v2, 1, v68
	v_mov_b32_e32 v3, v167
	s_add_u32 s6, s6, s12
	v_lshl_add_u64 v[32:33], v[0:1], 0, v[2:3]
	s_mov_b32 s27, 0x38000
	s_addc_u32 s7, s7, 0
	v_lshlrev_b32_e32 v168, 4, v160
	v_mov_b32_e32 v169, v167
	v_add_co_u32_e32 v12, vcc, s27, v32
	v_lshl_add_u64 v[40:41], s[6:7], 0, v[168:169]
	s_nop 0
	v_addc_co_u32_e32 v13, vcc, 0, v33, vcc
	s_movk_i32 s28, 0x2000
	v_add_co_u32_e32 v16, vcc, s28, v40
	s_mov_b32 s29, 0x70000
	s_nop 0
	v_addc_co_u32_e32 v17, vcc, 0, v41, vcc
	v_add_co_u32_e32 v24, vcc, s29, v32
	s_movk_i32 s30, 0x4000
	s_nop 0
	v_addc_co_u32_e32 v25, vcc, 0, v33, vcc
	v_lshlrev_b32_e32 v70, 4, v42
	v_mov_b32_e32 v71, v167
	v_add_co_u32_e32 v28, vcc, s30, v40
	v_lshl_add_u64 v[42:43], s[8:9], 0, v[70:71]
	s_movk_i32 s26, 0x1c00
	v_addc_co_u32_e32 v29, vcc, 0, v41, vcc
	s_mov_b32 s12, 0xa8000
	v_or_b32_e32 v42, v42, v162
	v_mov_b64_e32 v[44:45], s[0:1]
	v_add_co_u32_e32 v36, vcc, s12, v32
	v_mad_u64_u32 v[44:45], s[8:9], v42, s26, v[44:45]
	s_mov_b32 s5, 0
	v_addc_co_u32_e32 v37, vcc, 0, v33, vcc
	s_movk_i32 s31, 0x6000
	v_mad_i32_i24 v45, v43, s26, v45
	v_add_co_u32_e32 v40, vcc, s31, v40
	v_lshl_add_u64 v[42:43], v[44:45], 0, s[4:5]
	v_and_b32_e32 v74, 48, v160
	v_mov_b32_e32 v75, v167
	v_addc_co_u32_e32 v41, vcc, 0, v41, vcc
	v_lshl_add_u64 v[60:61], v[42:43], 0, v[74:75]
	global_load_dwordx4 v[0:3], v[32:33], off offset:1024
	global_load_dwordx4 v[4:7], v[32:33], off offset:2048
	global_load_dwordx4 v[8:11], v[12:13], off offset:1024
	s_nop 0
	global_load_dwordx4 v[12:15], v[12:13], off offset:2048
	s_nop 0
	global_load_dwordx4 v[16:19], v[16:17], off
	s_nop 0
	global_load_dwordx4 v[20:23], v[24:25], off offset:1024
	s_nop 0
	global_load_dwordx4 v[24:27], v[24:25], off offset:2048
	s_nop 0
	global_load_dwordx4 v[28:31], v[28:29], off
	s_nop 0
	global_load_dwordx4 v[32:35], v[36:37], off offset:1024
	s_nop 0
	global_load_dwordx4 v[36:39], v[36:37], off offset:2048
	s_nop 0
	global_load_dwordx4 v[40:43], v[40:41], off
	s_nop 0
	global_load_dwordx4 v[44:47], v[60:61], off
	global_load_dwordx4 v[48:51], v[60:61], off offset:64
	global_load_dwordx4 v[52:55], v[60:61], off offset:128
	global_load_dwordx4 v[56:59], v168, s[6:7]
	s_nop 0
	global_load_dwordx4 v[60:63], v[60:61], off offset:192
	v_bfe_u32 v69, v160, 4, 2
	v_lshlrev_b32_e32 v66, 3, v160
	v_bfe_u32 v65, v160, 2, 2
	v_lshlrev_b32_e32 v72, 3, v69
	v_and_b32_e32 v71, 24, v66
	v_and_b32_e32 v67, 63, v160
	v_lshlrev_b32_e32 v64, 3, v162
	v_lshl_or_b32 v185, v69, 2, v70
	v_add_u32_e32 v77, v73, v72
	v_or_b32_e32 v65, v72, v65
	v_add_u32_e32 v73, v73, v71
	v_add_u32_e32 v79, 0, v71
	v_add_u32_e32 v80, s10, v166
	v_or_b32_e32 v170, v70, v162
	v_lshl_add_u64 v[70:71], s[22:23], 0, v[166:167]
	s_mov_b64 s[6:7], 0x30bc000
	s_movk_i32 s4, 0x130
	v_add_u32_e32 v174, 32, v164
	v_mov_b32_e32 v83, 0x2600
	v_add_u32_e32 v76, 0x200, v160
	v_or_b32_e32 v78, 0x400, v160
	v_add_u32_e32 v89, 0x600, v160
	v_add_u32_e32 v75, 0, v166
	v_add_u32_e32 v69, 0, v74
	v_mad_i32_i24 v81, v162, -14, v80
	v_lshl_add_u64 v[172:173], v[70:71], 0, s[6:7]
	v_mul_u32_u24_e32 v71, 0x110, v164
	v_mul_u32_u24_e32 v82, 0x130, v164
	v_mad_u32_u24 v84, v164, s4, v83
	v_mul_u32_u24_e32 v70, 0xe00, v174
	v_mul_u32_u24_e32 v85, 0x130, v162
	v_or_b32_e32 v180, 16, v162
	v_or_b32_e32 v182, 32, v162
	v_or_b32_e32 v184, 48, v162
	v_or_b32_e32 v186, 64, v162
	v_or_b32_e32 v188, 0x50, v162
	v_or_b32_e32 v190, 0x60, v162
	v_or_b32_e32 v192, 0x70, v162
	v_mul_u32_u24_e32 v86, 40, v162
	v_lshlrev_b32_e32 v74, 3, v76
	v_lshlrev_b32_e32 v87, 4, v76
	v_lshlrev_b32_e32 v76, 3, v78
	v_lshlrev_b32_e32 v88, 4, v78
	v_lshlrev_b32_e32 v78, 3, v89
	v_lshlrev_b32_e32 v89, 4, v89
	v_mul_u32_u24_e32 v90, 40, v65
	v_mul_u32_u24_e32 v91, 0x130, v65
	v_mad_u32_u24 v65, v65, s4, v83
	v_lshlrev_b32_e32 v187, 4, v67
	v_mul_u32_u24_e32 v67, 0x110, v174
	v_mul_u32_u24_e32 v83, 0x110, v185
	v_lshlrev_b32_e32 v166, 1, v64
	v_mbcnt_lo_u32_b32 v64, -1, 0
	v_mov_b32_e32 v171, v167
	v_or_b32_e32 v176, 64, v164
	v_add_u32_e32 v178, 0x60, v164
	v_mov_b32_e32 v179, v167
	v_mov_b32_e32 v161, v162
	v_mov_b32_e32 v163, v180
	v_mov_b32_e32 v165, v182
	v_mov_b32_e32 v169, v184
	v_mov_b32_e32 v175, v186
	v_mov_b32_e32 v177, v188
	v_mov_b32_e32 v181, v190
	v_mov_b32_e32 v183, v192
	s_mov_b32 s38, 0x3f2aaaab
	v_mov_b32_e32 v189, 0x3ecc95a3
	s_mov_b32 s39, 0x3f317218
	s_mov_b32 s40, 0xff800000
	s_mov_b32 s41, 0x33800000
	v_add_u32_e32 v191, v75, v82
	s_add_i32 s42, 0, 0x13000
	v_add_u32_e32 v193, v75, v84
	v_lshlrev_b32_e32 v194, 1, v68
	v_lshlrev_b32_e32 v196, 1, v70
	v_add_u32_e32 v204, v69, v85
	v_add_u32_e32 v205, v77, v86
	v_lshlrev_b32_e32 v198, 1, v66
	v_lshlrev_b32_e32 v206, 1, v74
	v_add_u32_e32 v207, 0, v87
	v_lshlrev_b32_e32 v208, 1, v76
	v_add_u32_e32 v209, 0, v88
	v_lshlrev_b32_e32 v210, 1, v78
	v_add_u32_e32 v211, 0, v89
	v_add_u32_e32 v212, v73, v90
	v_add_u32_e32 v213, v79, v91
	v_add_u32_e32 v214, v79, v65
	s_mov_b64 s[6:7], 0x38000
	s_mov_b64 s[8:9], 0x70000
	v_lshlrev_b32_e32 v200, 1, v72
	v_mbcnt_hi_u32_b32 v215, -1, v64
	v_add_u32_e32 v216, v81, v83
	s_brev_b32 s10, 60
	s_mov_b32 s12, 0x358637bd
	s_mov_b32 s43, 0x800000
	s_movk_i32 s44, 0x7fff
	v_mov_b32_e32 v202, 0x3f317218
	v_mov_b32_e32 v217, 0x7f800000
	v_mov_b32_e32 v218, 0x7fc00000
	v_mov_b32_e32 v219, 0xff800000
	v_add_u32_e32 v220, v80, v71
	v_add_u32_e32 v221, v80, v67
	s_mov_b32 s45, s20
	s_bfe_u32 s98, s45, 0x20005
	s_lshl_b32 s98, s98, 2
	v_mov_b32_e32 v241, s98
	global_load_dword v242, v241, s[54:55]
	global_load_dword v243, v241, s[54:55] offset:16
	s_branch .LBB0_903

.LBB0_905:
	s_cmp_eq_u32 s100, 2
	s_cbranch_scc1 .LBB0_945
	s_cmp_lt_i32 s92, 6
	s_cselect_b64 s[4:5], -1, 0
	s_cmpk_lt_i32 s20, 0x200
	s_cselect_b64 s[0:1], -1, 0
	s_and_b64 s[4:5], s[4:5], s[0:1]
	s_and_b64 s[2:3], s[4:5], s[2:3]
	s_andn2_b64 vcc, exec, s[2:3]
	s_cbranch_vccnz .LBB0_945
	s_waitcnt vmcnt(0)
	v_or_b32_e32 v1, 0x400, v160
	v_sub_u32_e32 v4, 0x1010, v1
	v_or_b32_e32 v1, 0x800, v160
	v_sub_u32_e32 v8, 0x1010, v1
	v_or_b32_e32 v1, 0xc00, v160
	v_sub_u32_e32 v12, 0x1010, v1
	v_sub_u32_e32 v1, 0x210, v160
	v_sub_u32_e32 v3, 0, v1
	s_movk_i32 s2, 0x211
	v_max_i32_e32 v162, v1, v3
	v_mov_b32_e32 v1, 0x800000
	v_cmp_gt_u32_e32 vcc, s2, v160
	v_or_b32_e32 v3, 0x1000, v160
	s_movk_i32 s2, 0x1011
	v_cndmask_b32_e64 v164, v1, 0, vcc
	v_cmp_gt_u32_e32 vcc, s2, v3
	v_sub_u32_e32 v5, 0x1010, v3
	s_movk_i32 s10, 0x2018
	v_cndmask_b32_e64 v168, v1, 0, vcc
	v_or_b32_e32 v1, 0x2000, v160
	v_sub_u32_e32 v7, 0, v5
	v_cmp_gt_u32_e64 s[10:11], s10, v1
	v_lshrrev_b32_e32 v1, 5, v160
	v_max_i32_e32 v166, v5, v7
	v_and_b32_e32 v5, 31, v160
	v_and_b32_e32 v9, 30, v1
	v_mul_i32_i24_e32 v11, 0xffffff00, v9
	v_lshlrev_b32_e32 v170, 3, v5
	v_sub_u32_e32 v3, 0x1010, v160
	v_bfe_u32 v7, v160, 5, 1
	v_sub_u32_e32 v11, v11, v170
	v_mov_b32_e32 v0, 0
	v_min_u32_e32 v18, 0xfff, v3
	v_bfe_u32 v3, v160, 5, 3
	v_lshlrev_b32_e32 v13, 4, v7
	v_lshlrev_b32_e32 v11, 1, v11
	s_movk_i32 s12, 0x410
	v_lshlrev_b32_e32 v20, 13, v3
	v_mov_b32_e32 v21, v0
	v_add3_u32 v201, 0, v11, v13
	v_and_b32_e32 v11, 7, v160
	s_add_u32 s42, s22, 0x1cb6000
	v_mad_u32_u24 v196, v5, s12, v13
	v_lshl_add_u64 v[20:21], s[22:23], 0, v[20:21]
	s_mov_b64 s[12:13], 0x194bc000
	v_lshlrev_b32_e32 v13, 9, v160
	v_lshlrev_b32_e32 v24, 1, v11
	v_mov_b32_e32 v25, v0
	s_addc_u32 s43, s23, 0
	v_lshl_add_u64 v[174:175], v[20:21], 0, s[12:13]
	s_movk_i32 s26, 0x2080
	v_and_b32_e32 v20, 0x3000, v13
	v_lshlrev_b32_e32 v22, 5, v7
	v_lshl_add_u64 v[24:25], s[22:23], 0, v[24:25]
	s_mov_b64 s[28:29], 0x1b4bc000
	v_mov_b32_e32 v7, 0x100
	s_add_u32 s44, s22, 0x2cb6000
	v_sub_u32_e32 v2, 0xe10, v160
	v_sub_u32_e32 v6, 0xa10, v160
	v_sub_u32_e32 v10, 0x610, v160
	s_movk_i32 s8, 0x20f
	v_min_u32_e32 v14, 0x20f, v160
	v_min_u32_e32 v16, 15, v160
	s_movk_i32 s6, 0x218
	v_cmp_lt_u32_e64 s[12:13], 1, v5
	v_cmp_ne_u32_e64 s[14:15], 0, v5
	s_movk_i32 s16, 0xff
	v_mul_u32_u24_e32 v197, 0x2080, v3
	v_mad_u32_u24 v3, v3, s26, 0
	v_lshlrev_b32_e32 v198, 4, v5
	v_mad_u32_u24 v5, v1, s26, 0
	v_lshl_add_u64 v[176:177], v[24:25], 0, s[28:29]
	v_lshlrev_b32_e32 v24, 8, v9
	v_or_b32_e32 v26, 0x4000, v20
	v_lshl_or_b32 v28, v1, 8, v7
	s_addc_u32 s45, s23, 0
	s_mov_b32 s27, 0
	s_mov_b32 s46, 0x800000
	v_mov_b32_e32 v165, v0
	v_mov_b32_e32 v163, v0
	s_movk_i32 s47, 0x1000
	v_mov_b32_e32 v169, v0
	v_mov_b32_e32 v167, v0
	v_mov_b32_e32 v161, v0
	v_cmp_lt_u32_e64 s[2:3], 15, v160
	v_cmp_gt_u32_e64 s[4:5], 17, v160
	v_lshl_add_u32 v171, v160, 1, 0
	v_cmp_gt_u32_e64 s[6:7], s6, v160
	v_cmp_lt_u32_e64 s[8:9], s8, v160
	v_add_u32_e32 v172, -16, v170
	v_mov_b32_e32 v173, v0
	v_cmp_lt_u32_e64 s[16:17], s16, v160
	v_mul_u32_u24_e32 v199, 0x2080, v1
	v_add_u32_e32 v200, 0x3f0, v170
	v_lshlrev_b32_e32 v202, 2, v2
	v_lshlrev_b32_e32 v203, 2, v4
	v_lshlrev_b32_e32 v204, 2, v6
	v_lshlrev_b32_e32 v205, 2, v8
	v_lshlrev_b32_e32 v206, 2, v10
	v_lshlrev_b32_e32 v207, 2, v12
	s_mov_b32 s48, 0x801000
	s_mov_b32 s49, 0x802000
	v_lshlrev_b32_e32 v178, 2, v16
	v_lshlrev_b32_e32 v208, 2, v18
	s_movk_i32 s52, 0x7fff
	v_lshlrev_b32_e32 v180, 2, v14
	v_add_u32_e32 v209, v3, v198
	s_mov_b32 s53, 0x1000706
	v_add_u32_e32 v210, v5, v198
	s_movk_i32 s54, 0xff8
	s_movk_i32 s55, 0xf00
	s_movk_i32 s56, 0xef8
	v_lshlrev_b32_e32 v182, 1, v24
	v_lshlrev_b32_e32 v184, 1, v20
	v_lshlrev_b32_e32 v186, 1, v22
	v_lshlrev_b32_e32 v188, 1, v26
	v_lshlrev_b32_e32 v190, 1, v28
	v_mov_b32_e32 v179, v0
	s_mov_b32 s38, s20
	s_branch .LBB0_908

.LBB0_945:
	s_cmp_lg_u32 s100, 1
	s_cbranch_scc1 .Lp6_join0
	s_mov_b32 s100, 2
	v_readlane_b32 s54, v254, 0
	v_readlane_b32 s55, v254, 1
	v_readlane_b32 s56, v254, 2
	v_readlane_b32 s57, v254, 3
	s_waitcnt vmcnt(0) lgkmcnt(0)
	s_barrier
	s_nop 4
	s_branch .Lp6_retout_entry
.Lp6_join0:
	s_cmp_lg_u32 s100, 2
	s_cbranch_scc1 .Lp6_join
	s_cmpk_lt_i32 s20, 0x200
	s_cselect_b64 s[0:1], -1, 0
